# hand-written QKV GEMM epilogue (scalar destination selection, strided 32-bit offsets, rstd loaded once): ~8x fewer instructions than the exec-masked compiler version
# baseline (speedup 1.0000x reference)
;   DI void operator()(const f32x4 (&acc)[2][2][4][2], const pg8::Unit& u, int wr, int wc, int fr, int fq) const {
;     { int t_ = threadIdx.x; asm volatile("" : "+v"(t_)); fr = t_ & 15; fq = (t_ >> 4) & 3; }
;     switch (mode) {
;       case EM_BF16: run<EM_BF16>(acc, u, wr, wc, fr, fq); break;
;       case EM_RELU2: run<EM_RELU2>(acc, u, wr, wc, fr, fq); break;
;       case EM_F32: run<EM_F32>(acc, u, wr, wc, fr, fq); break;
;       case EM_QKV: run<EM_QKV>(acc, u, wr, wc, fr, fq); break;
;       case EM_SPLIT: run<EM_SPLIT>(acc, u, wr, wc, fr, fq); break;
;       case EM_TAIL: run<EM_TAIL>(acc, u, wr, wc, fr, fq); break;
;       default: run<EM_QROPE>(acc, u, wr, wc, fr, fq); break;
;     }
.LBB0_490:
	v_mov_b32_e32 v112, v181
	s_cmp_lt_i32 s71, 3
	v_and_b32_e32 v179, 15, v112
	v_bfe_u32 v178, v112, 4, 2
	s_cmp_eq_u32 s71, 1
	s_cbranch_scc1 .Lepi_qkv
	s_cmp_eq_u32 s71, 2
	s_cbranch_scc1 .Lepi_relu2
	s_cmp_eq_u32 s71, 0
	s_cbranch_scc1 .Lepi_plain
	s_cmp_eq_u32 s71, 6
	s_cbranch_scc1 .Lepi_plain
	s_cmp_lt_i32 s71, 3
	s_mov_b64 s[20:21], -1
	s_cbranch_scc1 .LBB0_668
	s_mov_b64 s[46:47], 0
	s_cmp_lt_i32 s71, 5
	s_mov_b64 s[48:49], 0
	s_cbranch_scc1 .LBB0_631
	s_cmp_gt_i32 s71, 5
	s_cbranch_scc0 .LBB0_560
	s_cmp_eq_u32 s71, 6
	s_mov_b64 s[48:49], -1
	s_cbranch_scc0 .LBB0_559
	s_lshl_b32 s40, s83, 8
	v_or_b32_e32 v112, s78, v179
	s_cmp_lt_u32 s64, 16
	v_add_u32_e32 v136, s40, v112
	s_cselect_b64 s[24:25], -1, 0
	v_ashrrev_i32_e32 v137, 31, v136
	s_and_b64 vcc, exec, s[24:25]
	s_cbranch_vccz .LBB0_496
	v_mul_lo_u32 v138, s89, v136
	v_mul_lo_u32 v139, s88, v137
	v_mad_u64_u32 v[134:135], s[20:21], s88, v136, 0
	v_add3_u32 v135, v135, v139, v138
	v_cvt_pk_bf16_f32 v130, v126, v127
	v_cvt_pk_bf16_f32 v131, v128, v129
	v_cvt_pk_bf16_f32 v132, v122, v123
	v_cvt_pk_bf16_f32 v133, v124, v125
	v_lshl_add_u64 v[140:141], v[134:135], 1, s[90:91]
	s_mov_b64 s[20:21], 0

; DI u32x4 pack8(f32x4 a, f32x4 b) { u32x4 w; w.x = cvtpk(a.x, a.y); w.y = cvtpk(a.z, a.w); w.z = cvtpk(b.x, b.y); w.w = cvtpk(b.z, b.w); return w; }
;   template <int MODE> DI void store8(int row, int col, f32x4 v0, f32x4 v1, int part) const {
;     if (MODE == EM_QKV || MODE == EM_RELU2 || MODE == EM_F32) { const float r_ = rs[row]; v0 *= r_; v1 *= r_; }
;     ...
;     else if (MODE == EM_QKV) {
;       const u32x4 w = pack8(v0, v1);
;       if (col < 2048) { *(u32x4*)((bf16*)(ws + A_Q0) + (size_t)row * 2048 + col) = w; }
;       else {
;         const int isv = col >= 4096; const int c = col - (isv ? 4096 : 2048);
;         if (row < NPR) {
;           *(u32x4*)((bf16*)(ws + (isv ? A_VP : A_KP)) + (size_t)row * 2048 + c) = w;
;           const int s = row & 4095, b = row >> 12;
;           if (s >= 3584) { float* p = outp + (isv ? O_AVP : O_AKP) + ((size_t)(b * 512 + s - 3584)) * 2048 + c; *(f32x4*)p = v0; *(f32x4*)(p + 4) = v1; }
;         } else {
;           const int rs = row - NPR, b = rs >> 6, i = rs & 63;
;           *(u32x4*)((bf16*)(ws + (isv ? A_VS : A_KS)) + ((size_t)(b * 576 + 512 + i)) * 2048 + c) = w;
;           float* p = outp + (isv ? O_AVS : O_AKS) + (size_t)rs * 2048 + c; *(f32x4*)p = v0; *(f32x4*)(p + 4) = v1;
;         }
;       }
.Lepi_qkv:
	v_or_b32_e32 v130, s78, v179
	v_lshl_add_u32 v130, s83, 8, v130
	v_lshlrev_b32_e32 v133, 2, v130
	global_load_dword v188, v133, s[96:97]
	global_load_dword v189, v133, s[96:97] offset:64
	global_load_dword v190, v133, s[96:97] offset:128
	global_load_dword v191, v133, s[96:97] offset:192
	global_load_dword v192, v133, s[96:97] offset:512
	global_load_dword v193, v133, s[96:97] offset:576
	global_load_dword v194, v133, s[96:97] offset:640
	global_load_dword v195, v133, s[96:97] offset:704
	s_lshr_b32 s20, s66, 3
	s_and_b32 s21, s66, 7
	s_lshl_b32 s21, s21, 8
	s_add_i32 s21, s21, s79
	s_lshl_b32 s22, s83, 8
	s_add_i32 s22, s22, s78
	s_mov_b32 s24, 0x50000
	s_mov_b32 s25, 0
	s_mov_b32 s44, 0
	s_cmp_lt_u32 s83, 64
	s_cselect_b32 s23, 1, 0
	s_cmp_eq_u32 s20, 0
	s_cselect_b32 s41, 1, s23
	s_cmp_eq_u32 s41, 0
	s_cbranch_scc1 .Lepi_qkv_smp
	s_lshl_b32 s40, s22, 12
	s_lshl_b32 s41, s21, 1
	s_add_i32 s40, s40, s41
	s_mov_b32 s41, 0xfc00000
	s_cmp_eq_u32 s20, 1
	s_cselect_b32 s41, 0x14000000, s41
	s_cmp_eq_u32 s20, 2
	s_cselect_b32 s41, 0x18000000, s41
	s_add_i32 s40, s40, s41
	s_cmp_eq_u32 s20, 0
	s_cbranch_scc1 .Lepi_qkv_addr
	s_and_b32 s45, s83, 15
	s_cmp_lt_u32 s45, 14
	s_cbranch_scc1 .Lepi_qkv_addr
	s_mov_b32 s25, 1
	s_sub_i32 s45, s45, 14
	s_lshl_b32 s45, s45, 8
	s_lshr_b32 s46, s83, 4
	s_lshl_b32 s46, s46, 9
	s_add_i32 s45, s45, s46
	s_add_i32 s45, s45, s78
	s_lshl_b32 s44, s45, 13
	s_lshl_b32 s45, s21, 2
	s_add_i32 s44, s44, s45
	s_mov_b32 s45, 0x9800000
	s_cmp_eq_u32 s20, 1
	s_cselect_b32 s45, 0x8800000, s45
	s_add_i32 s44, s44, s45
	s_branch .Lepi_qkv_addr
.Lepi_qkv_smp:
	s_sub_i32 s45, s83, 64
	s_lshl_b32 s46, s45, 2
	s_lshr_b32 s47, s78, 6
	s_add_i32 s46, s46, s47
	s_mul_i32 s46, s46, 0x240
	s_addk_i32 s46, 0x200
	s_lshl_b32 s46, s46, 12
	s_lshl_b32 s41, s21, 1
	s_add_i32 s40, s46, s41
	s_mov_b32 s41, 0x1e400000
	s_cmp_eq_u32 s20, 1
	s_cselect_b32 s41, 0x1c000000, s41
	s_add_i32 s40, s40, s41
	s_mov_b32 s24, 0x450000
	s_mov_b32 s25, 1
	s_lshl_b32 s45, s45, 8
	s_add_i32 s45, s45, s78
	s_lshl_b32 s44, s45, 13
	s_lshl_b32 s45, s21, 2
	s_add_i32 s44, s44, s45
	s_mov_b32 s45, 0xb000000
	s_cmp_eq_u32 s20, 1
	s_cselect_b32 s45, 0xa800000, s45
	s_add_i32 s44, s44, s45
.Lepi_qkv_addr:
	v_lshlrev_b32_e32 v131, 12, v179
	v_lshl_add_u32 v131, v178, 4, v131
	v_add_u32_e32 v131, s40, v131
	v_lshlrev_b32_e32 v132, 13, v179
	v_lshl_add_u32 v132, v178, 5, v132
	v_add_u32_e32 v132, s44, v132
	s_waitcnt vmcnt(0)
	s_cmp_eq_u32 s25, 0
	s_cbranch_scc1 .Lepi_qkv_nof32
	v_mov_b32_e32 v112, v188
	v_pk_mul_f32 v[126:127], v[126:127], v[112:113] op_sel_hi:[1,0]
	v_pk_mul_f32 v[128:129], v[128:129], v[112:113] op_sel_hi:[1,0]
	v_pk_mul_f32 v[122:123], v[122:123], v[112:113] op_sel_hi:[1,0]
	v_pk_mul_f32 v[124:125], v[124:125], v[112:113] op_sel_hi:[1,0]
	v_cvt_pk_bf16_f32 v136, v126, v127
	v_cvt_pk_bf16_f32 v137, v128, v129
	v_cvt_pk_bf16_f32 v138, v122, v123
	v_cvt_pk_bf16_f32 v139, v124, v125
	global_store_dwordx4 v131, v[136:139], s[54:55]
	global_store_dwordx4 v132, v[126:129], s[52:53] offset:0
	global_store_dwordx4 v132, v[122:125], s[52:53] offset:16
	v_pk_mul_f32 v[118:119], v[118:119], v[112:113] op_sel_hi:[1,0]
	v_pk_mul_f32 v[120:121], v[120:121], v[112:113] op_sel_hi:[1,0]
	v_pk_mul_f32 v[114:115], v[114:115], v[112:113] op_sel_hi:[1,0]
	v_pk_mul_f32 v[116:117], v[116:117], v[112:113] op_sel_hi:[1,0]
	v_cvt_pk_bf16_f32 v154, v118, v119
	v_cvt_pk_bf16_f32 v155, v120, v121
	v_cvt_pk_bf16_f32 v156, v114, v115
	v_cvt_pk_bf16_f32 v157, v116, v117
	global_store_dwordx4 v131, v[154:157], s[54:55] offset:256
	global_store_dwordx4 v132, v[118:121], s[52:53] offset:512
	global_store_dwordx4 v132, v[114:117], s[52:53] offset:528
	v_add_u32_e32 v131, 0x10000, v131
	v_add_u32_e32 v132, 0x20000, v132
	v_mov_b32_e32 v112, v189
	v_pk_mul_f32 v[108:109], v[108:109], v[112:113] op_sel_hi:[1,0]
	v_pk_mul_f32 v[110:111], v[110:111], v[112:113] op_sel_hi:[1,0]
	v_pk_mul_f32 v[104:105], v[104:105], v[112:113] op_sel_hi:[1,0]
	v_pk_mul_f32 v[106:107], v[106:107], v[112:113] op_sel_hi:[1,0]
	v_cvt_pk_bf16_f32 v136, v108, v109
	v_cvt_pk_bf16_f32 v137, v110, v111
	v_cvt_pk_bf16_f32 v138, v104, v105
	v_cvt_pk_bf16_f32 v139, v106, v107
	global_store_dwordx4 v131, v[136:139], s[54:55]
	global_store_dwordx4 v132, v[108:111], s[52:53] offset:0
	global_store_dwordx4 v132, v[104:107], s[52:53] offset:16
	v_pk_mul_f32 v[100:101], v[100:101], v[112:113] op_sel_hi:[1,0]
	v_pk_mul_f32 v[102:103], v[102:103], v[112:113] op_sel_hi:[1,0]
	v_pk_mul_f32 v[96:97], v[96:97], v[112:113] op_sel_hi:[1,0]
	v_pk_mul_f32 v[98:99], v[98:99], v[112:113] op_sel_hi:[1,0]
	v_cvt_pk_bf16_f32 v154, v100, v101
	v_cvt_pk_bf16_f32 v155, v102, v103
	v_cvt_pk_bf16_f32 v156, v96, v97
	v_cvt_pk_bf16_f32 v157, v98, v99
	global_store_dwordx4 v131, v[154:157], s[54:55] offset:256
	global_store_dwordx4 v132, v[100:103], s[52:53] offset:512
	global_store_dwordx4 v132, v[96:99], s[52:53] offset:528
	v_add_u32_e32 v131, 0x10000, v131
	v_add_u32_e32 v132, 0x20000, v132
	v_mov_b32_e32 v112, v190
	v_pk_mul_f32 v[92:93], v[92:93], v[112:113] op_sel_hi:[1,0]
	v_pk_mul_f32 v[94:95], v[94:95], v[112:113] op_sel_hi:[1,0]
	v_pk_mul_f32 v[88:89], v[88:89], v[112:113] op_sel_hi:[1,0]
	v_pk_mul_f32 v[90:91], v[90:91], v[112:113] op_sel_hi:[1,0]
	v_cvt_pk_bf16_f32 v136, v92, v93
	v_cvt_pk_bf16_f32 v137, v94, v95
	v_cvt_pk_bf16_f32 v138, v88, v89
	v_cvt_pk_bf16_f32 v139, v90, v91
	global_store_dwordx4 v131, v[136:139], s[54:55]
	global_store_dwordx4 v132, v[92:95], s[52:53] offset:0
	global_store_dwordx4 v132, v[88:91], s[52:53] offset:16
	v_pk_mul_f32 v[84:85], v[84:85], v[112:113] op_sel_hi:[1,0]
; DI u32x4 pack8(f32x4 a, f32x4 b) { u32x4 w; w.x = cvtpk(a.x, a.y); w.y = cvtpk(a.z, a.w); w.z = cvtpk(b.x, b.y); w.w = cvtpk(b.z, b.w); return w; }
;   template <int MODE> DI void store8(int row, int col, f32x4 v0, f32x4 v1, int part) const {
;     if (MODE == EM_QKV || MODE == EM_RELU2 || MODE == EM_F32) { const float r_ = rs[row]; v0 *= r_; v1 *= r_; }
;     ...
;     else if (MODE == EM_QKV) {
;       const u32x4 w = pack8(v0, v1);
;       if (col < 2048) { *(u32x4*)((bf16*)(ws + A_Q0) + (size_t)row * 2048 + col) = w; }
;       else {
;         const int isv = col >= 4096; const int c = col - (isv ? 4096 : 2048);
;         if (row < NPR) {
;           *(u32x4*)((bf16*)(ws + (isv ? A_VP : A_KP)) + (size_t)row * 2048 + c) = w;
;           const int s = row & 4095, b = row >> 12;
;           if (s >= 3584) { float* p = outp + (isv ? O_AVP : O_AKP) + ((size_t)(b * 512 + s - 3584)) * 2048 + c; *(f32x4*)p = v0; *(f32x4*)(p + 4) = v1; }
;         } else {
;           const int rs = row - NPR, b = rs >> 6, i = rs & 63;
;           *(u32x4*)((bf16*)(ws + (isv ? A_VS : A_KS)) + ((size_t)(b * 576 + 512 + i)) * 2048 + c) = w;
;           float* p = outp + (isv ? O_AVS : O_AKS) + (size_t)rs * 2048 + c; *(f32x4*)p = v0; *(f32x4*)(p + 4) = v1;
;         }
;       }
	v_pk_mul_f32 v[86:87], v[86:87], v[112:113] op_sel_hi:[1,0]
	v_pk_mul_f32 v[80:81], v[80:81], v[112:113] op_sel_hi:[1,0]
	v_pk_mul_f32 v[82:83], v[82:83], v[112:113] op_sel_hi:[1,0]
	v_cvt_pk_bf16_f32 v154, v84, v85
	v_cvt_pk_bf16_f32 v155, v86, v87
	v_cvt_pk_bf16_f32 v156, v80, v81
	v_cvt_pk_bf16_f32 v157, v82, v83
	global_store_dwordx4 v131, v[154:157], s[54:55] offset:256
	global_store_dwordx4 v132, v[84:87], s[52:53] offset:512
	global_store_dwordx4 v132, v[80:83], s[52:53] offset:528
	v_add_u32_e32 v131, 0x10000, v131
	v_add_u32_e32 v132, 0x20000, v132
	v_mov_b32_e32 v112, v191
	v_pk_mul_f32 v[76:77], v[76:77], v[112:113] op_sel_hi:[1,0]
	v_pk_mul_f32 v[78:79], v[78:79], v[112:113] op_sel_hi:[1,0]
	v_pk_mul_f32 v[72:73], v[72:73], v[112:113] op_sel_hi:[1,0]
	v_pk_mul_f32 v[74:75], v[74:75], v[112:113] op_sel_hi:[1,0]
	v_cvt_pk_bf16_f32 v136, v76, v77
	v_cvt_pk_bf16_f32 v137, v78, v79
	v_cvt_pk_bf16_f32 v138, v72, v73
	v_cvt_pk_bf16_f32 v139, v74, v75
	global_store_dwordx4 v131, v[136:139], s[54:55]
	global_store_dwordx4 v132, v[76:79], s[52:53] offset:0
	global_store_dwordx4 v132, v[72:75], s[52:53] offset:16
	v_pk_mul_f32 v[68:69], v[68:69], v[112:113] op_sel_hi:[1,0]
	v_pk_mul_f32 v[70:71], v[70:71], v[112:113] op_sel_hi:[1,0]
	v_pk_mul_f32 v[64:65], v[64:65], v[112:113] op_sel_hi:[1,0]
	v_pk_mul_f32 v[66:67], v[66:67], v[112:113] op_sel_hi:[1,0]
	v_cvt_pk_bf16_f32 v154, v68, v69
	v_cvt_pk_bf16_f32 v155, v70, v71
	v_cvt_pk_bf16_f32 v156, v64, v65
	v_cvt_pk_bf16_f32 v157, v66, v67
	global_store_dwordx4 v131, v[154:157], s[54:55] offset:256
	global_store_dwordx4 v132, v[68:71], s[52:53] offset:512
	global_store_dwordx4 v132, v[64:67], s[52:53] offset:528
	v_add_u32_e32 v131, s24, v131
	v_add_u32_e32 v132, 0xa0000, v132
	v_mov_b32_e32 v112, v192
	v_pk_mul_f32 v[60:61], v[60:61], v[112:113] op_sel_hi:[1,0]
	v_pk_mul_f32 v[62:63], v[62:63], v[112:113] op_sel_hi:[1,0]
	v_pk_mul_f32 v[56:57], v[56:57], v[112:113] op_sel_hi:[1,0]
	v_pk_mul_f32 v[58:59], v[58:59], v[112:113] op_sel_hi:[1,0]
	v_cvt_pk_bf16_f32 v136, v60, v61
	v_cvt_pk_bf16_f32 v137, v62, v63
	v_cvt_pk_bf16_f32 v138, v56, v57
	v_cvt_pk_bf16_f32 v139, v58, v59
	global_store_dwordx4 v131, v[136:139], s[54:55]
	global_store_dwordx4 v132, v[60:63], s[52:53] offset:0
	global_store_dwordx4 v132, v[56:59], s[52:53] offset:16
	v_pk_mul_f32 v[52:53], v[52:53], v[112:113] op_sel_hi:[1,0]
	v_pk_mul_f32 v[54:55], v[54:55], v[112:113] op_sel_hi:[1,0]
	v_pk_mul_f32 v[48:49], v[48:49], v[112:113] op_sel_hi:[1,0]
	v_pk_mul_f32 v[50:51], v[50:51], v[112:113] op_sel_hi:[1,0]
	v_cvt_pk_bf16_f32 v154, v52, v53
	v_cvt_pk_bf16_f32 v155, v54, v55
	v_cvt_pk_bf16_f32 v156, v48, v49
	v_cvt_pk_bf16_f32 v157, v50, v51
	global_store_dwordx4 v131, v[154:157], s[54:55] offset:256
	global_store_dwordx4 v132, v[52:55], s[52:53] offset:512
	global_store_dwordx4 v132, v[48:51], s[52:53] offset:528
	v_add_u32_e32 v131, 0x10000, v131
	v_add_u32_e32 v132, 0x20000, v132
	v_mov_b32_e32 v112, v193
	v_pk_mul_f32 v[44:45], v[44:45], v[112:113] op_sel_hi:[1,0]
	v_pk_mul_f32 v[46:47], v[46:47], v[112:113] op_sel_hi:[1,0]
	v_pk_mul_f32 v[40:41], v[40:41], v[112:113] op_sel_hi:[1,0]
	v_pk_mul_f32 v[42:43], v[42:43], v[112:113] op_sel_hi:[1,0]
	v_cvt_pk_bf16_f32 v136, v44, v45
	v_cvt_pk_bf16_f32 v137, v46, v47
	v_cvt_pk_bf16_f32 v138, v40, v41
	v_cvt_pk_bf16_f32 v139, v42, v43
	global_store_dwordx4 v131, v[136:139], s[54:55]
	global_store_dwordx4 v132, v[44:47], s[52:53] offset:0
	global_store_dwordx4 v132, v[40:43], s[52:53] offset:16
	v_pk_mul_f32 v[36:37], v[36:37], v[112:113] op_sel_hi:[1,0]
	v_pk_mul_f32 v[38:39], v[38:39], v[112:113] op_sel_hi:[1,0]
	v_pk_mul_f32 v[32:33], v[32:33], v[112:113] op_sel_hi:[1,0]
	v_pk_mul_f32 v[34:35], v[34:35], v[112:113] op_sel_hi:[1,0]
	v_cvt_pk_bf16_f32 v154, v36, v37
	v_cvt_pk_bf16_f32 v155, v38, v39
	v_cvt_pk_bf16_f32 v156, v32, v33
	v_cvt_pk_bf16_f32 v157, v34, v35
	global_store_dwordx4 v131, v[154:157], s[54:55] offset:256
	global_store_dwordx4 v132, v[36:39], s[52:53] offset:512
	global_store_dwordx4 v132, v[32:35], s[52:53] offset:528
	v_add_u32_e32 v131, 0x10000, v131
	v_add_u32_e32 v132, 0x20000, v132
	v_mov_b32_e32 v112, v194
	v_pk_mul_f32 v[28:29], v[28:29], v[112:113] op_sel_hi:[1,0]
	v_pk_mul_f32 v[30:31], v[30:31], v[112:113] op_sel_hi:[1,0]
	v_pk_mul_f32 v[24:25], v[24:25], v[112:113] op_sel_hi:[1,0]
	v_pk_mul_f32 v[26:27], v[26:27], v[112:113] op_sel_hi:[1,0]
	v_cvt_pk_bf16_f32 v136, v28, v29
	v_cvt_pk_bf16_f32 v137, v30, v31
	v_cvt_pk_bf16_f32 v138, v24, v25
	v_cvt_pk_bf16_f32 v139, v26, v27
	global_store_dwordx4 v131, v[136:139], s[54:55]
	global_store_dwordx4 v132, v[28:31], s[52:53] offset:0
	global_store_dwordx4 v132, v[24:27], s[52:53] offset:16
	v_pk_mul_f32 v[20:21], v[20:21], v[112:113] op_sel_hi:[1,0]
	v_pk_mul_f32 v[22:23], v[22:23], v[112:113] op_sel_hi:[1,0]
	v_pk_mul_f32 v[16:17], v[16:17], v[112:113] op_sel_hi:[1,0]
	v_pk_mul_f32 v[18:19], v[18:19], v[112:113] op_sel_hi:[1,0]
	v_cvt_pk_bf16_f32 v154, v20, v21
	v_cvt_pk_bf16_f32 v155, v22, v23
	v_cvt_pk_bf16_f32 v156, v16, v17
	v_cvt_pk_bf16_f32 v157, v18, v19
	global_store_dwordx4 v131, v[154:157], s[54:55] offset:256
	global_store_dwordx4 v132, v[20:23], s[52:53] offset:512
	global_store_dwordx4 v132, v[16:19], s[52:53] offset:528
	v_add_u32_e32 v131, 0x10000, v131
	v_add_u32_e32 v132, 0x20000, v132
	v_mov_b32_e32 v112, v195
	v_pk_mul_f32 v[12:13], v[12:13], v[112:113] op_sel_hi:[1,0]
	v_pk_mul_f32 v[14:15], v[14:15], v[112:113] op_sel_hi:[1,0]
	v_pk_mul_f32 v[8:9], v[8:9], v[112:113] op_sel_hi:[1,0]
	v_pk_mul_f32 v[10:11], v[10:11], v[112:113] op_sel_hi:[1,0]
	v_cvt_pk_bf16_f32 v136, v12, v13
	v_cvt_pk_bf16_f32 v137, v14, v15
	v_cvt_pk_bf16_f32 v138, v8, v9
	v_cvt_pk_bf16_f32 v139, v10, v11
	global_store_dwordx4 v131, v[136:139], s[54:55]
	global_store_dwordx4 v132, v[12:15], s[52:53] offset:0
	global_store_dwordx4 v132, v[8:11], s[52:53] offset:16
	v_pk_mul_f32 v[4:5], v[4:5], v[112:113] op_sel_hi:[1,0]
	v_pk_mul_f32 v[6:7], v[6:7], v[112:113] op_sel_hi:[1,0]
	v_pk_mul_f32 v[0:1], v[0:1], v[112:113] op_sel_hi:[1,0]
	v_pk_mul_f32 v[2:3], v[2:3], v[112:113] op_sel_hi:[1,0]
	v_cvt_pk_bf16_f32 v154, v4, v5
	v_cvt_pk_bf16_f32 v155, v6, v7
	v_cvt_pk_bf16_f32 v156, v0, v1
	v_cvt_pk_bf16_f32 v157, v2, v3
	global_store_dwordx4 v131, v[154:157], s[54:55] offset:256
	global_store_dwordx4 v132, v[4:7], s[52:53] offset:512
	global_store_dwordx4 v132, v[0:3], s[52:53] offset:528
	s_nop 1
	s_branch .LBB0_837
; DI u32x4 pack8(f32x4 a, f32x4 b) { u32x4 w; w.x = cvtpk(a.x, a.y); w.y = cvtpk(a.z, a.w); w.z = cvtpk(b.x, b.y); w.w = cvtpk(b.z, b.w); return w; }
;   template <int MODE> DI void store8(int row, int col, f32x4 v0, f32x4 v1, int part) const {
;     if (MODE == EM_QKV || MODE == EM_RELU2 || MODE == EM_F32) { const float r_ = rs[row]; v0 *= r_; v1 *= r_; }
;     ...
;     else if (MODE == EM_QKV) {
;       const u32x4 w = pack8(v0, v1);
;       if (col < 2048) { *(u32x4*)((bf16*)(ws + A_Q0) + (size_t)row * 2048 + col) = w; }
;       else {
;         const int isv = col >= 4096; const int c = col - (isv ? 4096 : 2048);
;         if (row < NPR) {
;           *(u32x4*)((bf16*)(ws + (isv ? A_VP : A_KP)) + (size_t)row * 2048 + c) = w;
.Lepi_qkv_nof32:
	v_mov_b32_e32 v112, v188
	v_pk_mul_f32 v[126:127], v[126:127], v[112:113] op_sel_hi:[1,0]
	v_pk_mul_f32 v[128:129], v[128:129], v[112:113] op_sel_hi:[1,0]
	v_pk_mul_f32 v[122:123], v[122:123], v[112:113] op_sel_hi:[1,0]
	v_pk_mul_f32 v[124:125], v[124:125], v[112:113] op_sel_hi:[1,0]
	v_cvt_pk_bf16_f32 v136, v126, v127
	v_cvt_pk_bf16_f32 v137, v128, v129
	v_cvt_pk_bf16_f32 v138, v122, v123
	v_cvt_pk_bf16_f32 v139, v124, v125
	global_store_dwordx4 v131, v[136:139], s[54:55]
	v_pk_mul_f32 v[118:119], v[118:119], v[112:113] op_sel_hi:[1,0]
	v_pk_mul_f32 v[120:121], v[120:121], v[112:113] op_sel_hi:[1,0]
	v_pk_mul_f32 v[114:115], v[114:115], v[112:113] op_sel_hi:[1,0]
	v_pk_mul_f32 v[116:117], v[116:117], v[112:113] op_sel_hi:[1,0]
	v_cvt_pk_bf16_f32 v154, v118, v119
	v_cvt_pk_bf16_f32 v155, v120, v121
	v_cvt_pk_bf16_f32 v156, v114, v115
	v_cvt_pk_bf16_f32 v157, v116, v117
	global_store_dwordx4 v131, v[154:157], s[54:55] offset:256
	v_add_u32_e32 v131, 0x10000, v131
	v_mov_b32_e32 v112, v189
	v_pk_mul_f32 v[108:109], v[108:109], v[112:113] op_sel_hi:[1,0]
	v_pk_mul_f32 v[110:111], v[110:111], v[112:113] op_sel_hi:[1,0]
	v_pk_mul_f32 v[104:105], v[104:105], v[112:113] op_sel_hi:[1,0]
	v_pk_mul_f32 v[106:107], v[106:107], v[112:113] op_sel_hi:[1,0]
	v_cvt_pk_bf16_f32 v136, v108, v109
	v_cvt_pk_bf16_f32 v137, v110, v111
	v_cvt_pk_bf16_f32 v138, v104, v105
	v_cvt_pk_bf16_f32 v139, v106, v107
	global_store_dwordx4 v131, v[136:139], s[54:55]
	v_pk_mul_f32 v[100:101], v[100:101], v[112:113] op_sel_hi:[1,0]
	v_pk_mul_f32 v[102:103], v[102:103], v[112:113] op_sel_hi:[1,0]
	v_pk_mul_f32 v[96:97], v[96:97], v[112:113] op_sel_hi:[1,0]
	v_pk_mul_f32 v[98:99], v[98:99], v[112:113] op_sel_hi:[1,0]
	v_cvt_pk_bf16_f32 v154, v100, v101
	v_cvt_pk_bf16_f32 v155, v102, v103
	v_cvt_pk_bf16_f32 v156, v96, v97
	v_cvt_pk_bf16_f32 v157, v98, v99
	global_store_dwordx4 v131, v[154:157], s[54:55] offset:256
	v_add_u32_e32 v131, 0x10000, v131
	v_mov_b32_e32 v112, v190
	v_pk_mul_f32 v[92:93], v[92:93], v[112:113] op_sel_hi:[1,0]
	v_pk_mul_f32 v[94:95], v[94:95], v[112:113] op_sel_hi:[1,0]
	v_pk_mul_f32 v[88:89], v[88:89], v[112:113] op_sel_hi:[1,0]
	v_pk_mul_f32 v[90:91], v[90:91], v[112:113] op_sel_hi:[1,0]
	v_cvt_pk_bf16_f32 v136, v92, v93
	v_cvt_pk_bf16_f32 v137, v94, v95
	v_cvt_pk_bf16_f32 v138, v88, v89
	v_cvt_pk_bf16_f32 v139, v90, v91
	global_store_dwordx4 v131, v[136:139], s[54:55]
	v_pk_mul_f32 v[84:85], v[84:85], v[112:113] op_sel_hi:[1,0]
	v_pk_mul_f32 v[86:87], v[86:87], v[112:113] op_sel_hi:[1,0]
	v_pk_mul_f32 v[80:81], v[80:81], v[112:113] op_sel_hi:[1,0]
	v_pk_mul_f32 v[82:83], v[82:83], v[112:113] op_sel_hi:[1,0]
	v_cvt_pk_bf16_f32 v154, v84, v85
	v_cvt_pk_bf16_f32 v155, v86, v87
	v_cvt_pk_bf16_f32 v156, v80, v81
	v_cvt_pk_bf16_f32 v157, v82, v83
	global_store_dwordx4 v131, v[154:157], s[54:55] offset:256
	v_add_u32_e32 v131, 0x10000, v131
	v_mov_b32_e32 v112, v191
	v_pk_mul_f32 v[76:77], v[76:77], v[112:113] op_sel_hi:[1,0]
	v_pk_mul_f32 v[78:79], v[78:79], v[112:113] op_sel_hi:[1,0]
	v_pk_mul_f32 v[72:73], v[72:73], v[112:113] op_sel_hi:[1,0]
	v_pk_mul_f32 v[74:75], v[74:75], v[112:113] op_sel_hi:[1,0]
	v_cvt_pk_bf16_f32 v136, v76, v77
	v_cvt_pk_bf16_f32 v137, v78, v79
	v_cvt_pk_bf16_f32 v138, v72, v73
	v_cvt_pk_bf16_f32 v139, v74, v75
	global_store_dwordx4 v131, v[136:139], s[54:55]
	v_pk_mul_f32 v[68:69], v[68:69], v[112:113] op_sel_hi:[1,0]
	v_pk_mul_f32 v[70:71], v[70:71], v[112:113] op_sel_hi:[1,0]
	v_pk_mul_f32 v[64:65], v[64:65], v[112:113] op_sel_hi:[1,0]
	v_pk_mul_f32 v[66:67], v[66:67], v[112:113] op_sel_hi:[1,0]
	v_cvt_pk_bf16_f32 v154, v68, v69
	v_cvt_pk_bf16_f32 v155, v70, v71
	v_cvt_pk_bf16_f32 v156, v64, v65
	v_cvt_pk_bf16_f32 v157, v66, v67
; DI u32x4 pack8(f32x4 a, f32x4 b) { u32x4 w; w.x = cvtpk(a.x, a.y); w.y = cvtpk(a.z, a.w); w.z = cvtpk(b.x, b.y); w.w = cvtpk(b.z, b.w); return w; }
;   template <int MODE> DI void store8(int row, int col, f32x4 v0, f32x4 v1, int part) const {
;     if (MODE == EM_QKV || MODE == EM_RELU2 || MODE == EM_F32) { const float r_ = rs[row]; v0 *= r_; v1 *= r_; }
;     ...
;     else if (MODE == EM_QKV) {
;       const u32x4 w = pack8(v0, v1);
;       if (col < 2048) { *(u32x4*)((bf16*)(ws + A_Q0) + (size_t)row * 2048 + col) = w; }
;       else {
;         const int isv = col >= 4096; const int c = col - (isv ? 4096 : 2048);
;         if (row < NPR) {
;           *(u32x4*)((bf16*)(ws + (isv ? A_VP : A_KP)) + (size_t)row * 2048 + c) = w;
	global_store_dwordx4 v131, v[154:157], s[54:55] offset:256
	v_add_u32_e32 v131, s24, v131
	v_mov_b32_e32 v112, v192
	v_pk_mul_f32 v[60:61], v[60:61], v[112:113] op_sel_hi:[1,0]
	v_pk_mul_f32 v[62:63], v[62:63], v[112:113] op_sel_hi:[1,0]
	v_pk_mul_f32 v[56:57], v[56:57], v[112:113] op_sel_hi:[1,0]
	v_pk_mul_f32 v[58:59], v[58:59], v[112:113] op_sel_hi:[1,0]
	v_cvt_pk_bf16_f32 v136, v60, v61
	v_cvt_pk_bf16_f32 v137, v62, v63
	v_cvt_pk_bf16_f32 v138, v56, v57
	v_cvt_pk_bf16_f32 v139, v58, v59
	global_store_dwordx4 v131, v[136:139], s[54:55]
	v_pk_mul_f32 v[52:53], v[52:53], v[112:113] op_sel_hi:[1,0]
	v_pk_mul_f32 v[54:55], v[54:55], v[112:113] op_sel_hi:[1,0]
	v_pk_mul_f32 v[48:49], v[48:49], v[112:113] op_sel_hi:[1,0]
	v_pk_mul_f32 v[50:51], v[50:51], v[112:113] op_sel_hi:[1,0]
	v_cvt_pk_bf16_f32 v154, v52, v53
	v_cvt_pk_bf16_f32 v155, v54, v55
	v_cvt_pk_bf16_f32 v156, v48, v49
	v_cvt_pk_bf16_f32 v157, v50, v51
	global_store_dwordx4 v131, v[154:157], s[54:55] offset:256
	v_add_u32_e32 v131, 0x10000, v131
	v_mov_b32_e32 v112, v193
	v_pk_mul_f32 v[44:45], v[44:45], v[112:113] op_sel_hi:[1,0]
	v_pk_mul_f32 v[46:47], v[46:47], v[112:113] op_sel_hi:[1,0]
	v_pk_mul_f32 v[40:41], v[40:41], v[112:113] op_sel_hi:[1,0]
	v_pk_mul_f32 v[42:43], v[42:43], v[112:113] op_sel_hi:[1,0]
	v_cvt_pk_bf16_f32 v136, v44, v45
	v_cvt_pk_bf16_f32 v137, v46, v47
	v_cvt_pk_bf16_f32 v138, v40, v41
	v_cvt_pk_bf16_f32 v139, v42, v43
	global_store_dwordx4 v131, v[136:139], s[54:55]
	v_pk_mul_f32 v[36:37], v[36:37], v[112:113] op_sel_hi:[1,0]
	v_pk_mul_f32 v[38:39], v[38:39], v[112:113] op_sel_hi:[1,0]
	v_pk_mul_f32 v[32:33], v[32:33], v[112:113] op_sel_hi:[1,0]
	v_pk_mul_f32 v[34:35], v[34:35], v[112:113] op_sel_hi:[1,0]
	v_cvt_pk_bf16_f32 v154, v36, v37
	v_cvt_pk_bf16_f32 v155, v38, v39
	v_cvt_pk_bf16_f32 v156, v32, v33
	v_cvt_pk_bf16_f32 v157, v34, v35
	global_store_dwordx4 v131, v[154:157], s[54:55] offset:256
	v_add_u32_e32 v131, 0x10000, v131
	v_mov_b32_e32 v112, v194
	v_pk_mul_f32 v[28:29], v[28:29], v[112:113] op_sel_hi:[1,0]
	v_pk_mul_f32 v[30:31], v[30:31], v[112:113] op_sel_hi:[1,0]
	v_pk_mul_f32 v[24:25], v[24:25], v[112:113] op_sel_hi:[1,0]
	v_pk_mul_f32 v[26:27], v[26:27], v[112:113] op_sel_hi:[1,0]
	v_cvt_pk_bf16_f32 v136, v28, v29
	v_cvt_pk_bf16_f32 v137, v30, v31
	v_cvt_pk_bf16_f32 v138, v24, v25
	v_cvt_pk_bf16_f32 v139, v26, v27
	global_store_dwordx4 v131, v[136:139], s[54:55]
	v_pk_mul_f32 v[20:21], v[20:21], v[112:113] op_sel_hi:[1,0]
	v_pk_mul_f32 v[22:23], v[22:23], v[112:113] op_sel_hi:[1,0]
	v_pk_mul_f32 v[16:17], v[16:17], v[112:113] op_sel_hi:[1,0]
	v_pk_mul_f32 v[18:19], v[18:19], v[112:113] op_sel_hi:[1,0]
	v_cvt_pk_bf16_f32 v154, v20, v21
	v_cvt_pk_bf16_f32 v155, v22, v23
	v_cvt_pk_bf16_f32 v156, v16, v17
	v_cvt_pk_bf16_f32 v157, v18, v19
	global_store_dwordx4 v131, v[154:157], s[54:55] offset:256
	v_add_u32_e32 v131, 0x10000, v131
	v_mov_b32_e32 v112, v195
	v_pk_mul_f32 v[12:13], v[12:13], v[112:113] op_sel_hi:[1,0]
	v_pk_mul_f32 v[14:15], v[14:15], v[112:113] op_sel_hi:[1,0]
	v_pk_mul_f32 v[8:9], v[8:9], v[112:113] op_sel_hi:[1,0]
	v_pk_mul_f32 v[10:11], v[10:11], v[112:113] op_sel_hi:[1,0]
	v_cvt_pk_bf16_f32 v136, v12, v13
	v_cvt_pk_bf16_f32 v137, v14, v15
	v_cvt_pk_bf16_f32 v138, v8, v9
	v_cvt_pk_bf16_f32 v139, v10, v11
	global_store_dwordx4 v131, v[136:139], s[54:55]
	v_pk_mul_f32 v[4:5], v[4:5], v[112:113] op_sel_hi:[1,0]
	v_pk_mul_f32 v[6:7], v[6:7], v[112:113] op_sel_hi:[1,0]
	v_pk_mul_f32 v[0:1], v[0:1], v[112:113] op_sel_hi:[1,0]
	v_pk_mul_f32 v[2:3], v[2:3], v[112:113] op_sel_hi:[1,0]
	v_cvt_pk_bf16_f32 v154, v4, v5
	v_cvt_pk_bf16_f32 v155, v6, v7
	v_cvt_pk_bf16_f32 v156, v0, v1
	v_cvt_pk_bf16_f32 v157, v2, v3
	global_store_dwordx4 v131, v[154:157], s[54:55] offset:256
	s_nop 1
	s_branch .LBB0_837
